# prologue S5 table rows: 24 serial load-wait-store steps replaced by one batch of loads and a single wait (plus SGPR-read spacing fix in the pass-B hint loads)
# speedup vs baseline: 1.0019x; 1.0019x over previous
; __device__ __forceinline__ unsigned pk2(float lo, float hi) { return pg8::cvt_pk_bf16(lo, hi); }
; __device__ __forceinline__ void prologue(const Args& a, LAS unsigned char* lds, int tid, int wave, int lane) {
;     ...
;         const float lre = a.in[I_LRE][i], lim = a.in[I_LIM][i], step = expf(a.in[I_LSTEP][l * NG + g]);
;         const float mag = expf(lre * step), ar = mag * cosf(lim * step), ai = mag * sinf(lim * step), den = lre * lre + lim * lim;
;         const float cr = ((ar - 1.f) * lre + ai * lim) / den, ci = (ai * lre - (ar - 1.f) * lim) / den;
;         float pr = ar, pi = ai;
; #pragma unroll
;         for (int k = 0; k < 8; ++k) { const float nr = pr * pr - pi * pi, ni = 2.f * pr * pi; pr = nr; pi = ni; }
;         ((f32x4*)(ws + WS_TA))[i] = (f32x4){ar, ai, pr, pi};
;         bf16_t* tbh = (bf16_t*)(ws + WS_TB) + (size_t)(l * NG + g) * 128 * GC;
;         const float* bre = a.in[I_BRE] + (size_t)i * GC; const float* bim = a.in[I_BIM] + (size_t)i * GC;
; #pragma unroll
;         for (int c = 0; c < GC; c += 2) { const float br0 = bre[c], bi0 = bim[c], br1 = bre[c + 1], bi1 = bim[c + 1];
;             *(unsigned*)(tbh + (2 * p) * GC + c) = pk2(cr * br0 - ci * bi0, cr * br1 - ci * bi1); *(unsigned*)(tbh + (2 * p + 1) * GC + c) = pk2(cr * bi0 + ci * br0, cr * bi1 + ci * br1); }
;         bf16_t* tc = (bf16_t*)(ws + WS_TC) + (size_t)(l * NG + g) * GC * 128;
;         const float* cre = a.in[I_CRE] + (size_t)(l * NG + g) * GC * NP; const float* cim = a.in[I_CIM] + (size_t)(l * NG + g) * GC * NP;
; #pragma unroll
;         for (int c = 0; c < GC; ++c) *(unsigned*)(tc + c * 128 + 2 * p) = pk2(cre[c * NP + p], -cim[c * NP + p]);
.LBB0_141:
	s_or_b64 exec, exec, s[0:1]
	s_waitcnt vmcnt(0)
	v_mul_f32_e32 v21, v19, v21
	v_mul_f32_e32 v24, 0x3fb8aa3b, v21
	v_fma_f32 v25, v21, s24, -v24
	v_rndne_f32_e32 v27, v24
	v_fmac_f32_e32 v25, 0x32a5705f, v21
	v_sub_f32_e32 v24, v24, v27
	v_add_f32_e32 v24, v24, v25
	v_cvt_i32_f32_e32 v25, v27
	v_exp_f32_e32 v24, v24
	v_cmp_ngt_f32_e32 vcc, s25, v21
	v_readlane_b32 s36, v252, 16
	v_readlane_b32 s37, v252, 17
	v_ldexp_f32 v24, v24, v25
	v_cndmask_b32_e32 v24, 0, v24, vcc
	v_cmp_nlt_f32_e32 vcc, s26, v21
	v_mul_f32_e32 v21, v23, v23
	v_lshlrev_b64 v[6:7], 12, v[6:7]
	v_cndmask_b32_e32 v34, v11, v24, vcc
	v_fmamk_f32 v24, v21, 0xb94c1982, v12
	v_fmaak_f32 v24, v21, v24, 0xbe2aaa9d
	v_mul_f32_e32 v24, v21, v24
	v_fmac_f32_e32 v23, v23, v24
	v_fmamk_f32 v24, v21, 0x37d75334, v13
	v_fmaak_f32 v24, v21, v24, 0x3d2aabf7
	v_fmaak_f32 v24, v21, v24, 0xbf000004
	v_fma_f32 v21, v21, v24, 1.0
	v_and_b32_e32 v24, 1, v22
	v_cmp_eq_u32_e32 vcc, 0, v24
	v_lshlrev_b32_e32 v22, 30, v22
	v_readlane_b32 s38, v252, 18
	v_cndmask_b32_e64 v21, -v23, v21, vcc
	v_bitop3_b32 v21, v22, v21, s64 bitop3:0x6c
	v_cmp_class_f32_e64 vcc, v5, s52
	v_xor_b32_e32 v5, v20, v5
	v_readlane_b32 s39, v252, 19
	v_cndmask_b32_e32 v35, v16, v21, vcc
	v_mul_f32_e32 v21, v26, v26
	v_fmamk_f32 v23, v21, 0xb94c1982, v12
	v_fmaak_f32 v23, v21, v23, 0xbe2aaa9d
	v_mul_f32_e32 v23, v21, v23
	v_fmac_f32_e32 v26, v26, v23
	v_fmamk_f32 v23, v21, 0x37d75334, v13
	v_fmaak_f32 v23, v21, v23, 0x3d2aabf7
	v_fmaak_f32 v23, v21, v23, 0xbf000004
	v_fma_f32 v21, v21, v23, 1.0
	v_and_b32_e32 v23, 1, v2
	v_lshlrev_b32_e32 v2, 30, v2
	v_cmp_eq_u32_e64 s[0:1], 0, v23
	v_and_b32_e32 v2, 0x80000000, v2
	v_xor_b32_e32 v2, v5, v2
	v_cndmask_b32_e64 v21, v21, v26, s[0:1]
	v_xor_b32_e32 v2, v2, v21
	v_mul_f32_e32 v22, v34, v35
	v_cndmask_b32_e32 v2, v16, v2, vcc
	v_mov_b32_e32 v5, v22
	v_mul_f32_e32 v26, v34, v2
	v_pk_mul_f32 v[20:21], v[22:23], v[4:5] op_sel_hi:[0,1]
	v_mul_f32_e32 v27, v26, v26
	v_pk_mul_f32 v[20:21], v[20:21], v[26:27]
	v_pk_fma_f32 v[24:25], v[22:23], v[4:5], v[26:27] op_sel_hi:[0,1,1] neg_lo:[0,0,1] neg_hi:[0,0,1]
	v_mov_b32_e32 v21, v25
	v_mul_f32_e32 v2, v25, v25
	v_pk_fma_f32 v[28:29], v[20:21], v[20:21], v[2:3] op_sel_hi:[1,1,0] neg_lo:[1,0,0] neg_hi:[1,0,0]
	v_add_f32_e32 v2, v25, v25
	v_mul_f32_e32 v29, v20, v2
	v_mul_f32_e32 v2, v29, v29
	v_pk_fma_f32 v[24:25], v[28:29], v[28:29], v[2:3] op_sel_hi:[1,1,0] neg_lo:[0,0,1] neg_hi:[0,0,1]
	v_add_f32_e32 v21, v28, v28
	v_mov_b32_e32 v28, v24
	v_mov_b32_e32 v20, v24
	v_pk_mul_f32 v[20:21], v[28:29], v[20:21]
	v_mov_b32_e32 v29, v4
	v_pk_mov_b32 v[24:25], v[20:21], v[24:25] op_sel:[1,0]
	v_mov_b32_e32 v28, v21
	v_pk_mul_f32 v[30:31], v[24:25], v[28:29]
	v_pk_fma_f32 v[24:25], v[24:25], v[28:29], v[20:21] neg_lo:[1,0,0] neg_hi:[1,0,0]
	v_pk_mul_f32 v[28:29], v[20:21], v[30:31]
	v_pk_mov_b32 v[20:21], v[20:21], v[24:25] op_sel:[1,0]
	v_mov_b32_e32 v30, v31
	v_mov_b32_e32 v31, v4
	v_pk_mul_f32 v[20:21], v[20:21], v[30:31]
	v_mov_b32_e32 v32, v24
	v_mov_b32_e32 v33, v29
	v_mov_b32_e32 v25, v21
	v_pk_mul_f32 v[24:25], v[32:33], v[24:25]
	v_pk_mul_f32 v[30:31], v[28:29], v[20:21]
	v_pk_fma_f32 v[20:21], v[28:29], v[20:21], v[24:25] op_sel:[1,0,0] neg_lo:[1,0,0] neg_hi:[1,0,0]
	v_pk_mul_f32 v[28:29], v[24:25], v[30:31]
	v_mov_b32_e32 v30, v20
	v_mov_b32_e32 v31, v4
	v_pk_mul_f32 v[32:33], v[20:21], v[30:31] op_sel_hi:[0,1]
	v_mov_b32_e32 v24, v29
	v_pk_fma_f32 v[20:21], v[20:21], v[30:31], v[24:25] op_sel_hi:[0,1,1] neg_lo:[0,0,1] neg_hi:[0,0,1]
	v_pk_mul_f32 v[24:25], v[32:33], v[24:25]
	v_add_f32_e32 v29, v20, v20
	v_mov_b32_e32 v21, v25
	v_mul_f32_e32 v2, v25, v25
	v_pk_fma_f32 v[20:21], v[20:21], v[20:21], v[2:3] op_sel_hi:[1,1,0] neg_lo:[0,0,1] neg_hi:[0,0,1]
	v_mov_b32_e32 v23, v26
	v_mov_b32_e32 v24, v20
	v_mov_b32_e32 v28, v20
	v_pk_mul_f32 v[28:29], v[24:25], v[28:29]
	v_mov_b32_e32 v25, v4
	v_pk_mov_b32 v[20:21], v[28:29], v[20:21] op_sel:[1,0]
	v_mov_b32_e32 v24, v29
	v_pk_add_f32 v[30:31], v[20:21], v[20:21]
	v_pk_fma_f32 v[24:25], v[20:21], v[24:25], v[28:29] neg_lo:[1,0,0] neg_hi:[1,0,0]
	v_pk_mul_f32 v[20:21], v[28:29], v[30:31]
	v_lshl_add_u64 v[28:29], v[0:1], 4, s[10:11]
	v_mov_b32_e32 v25, v21
	v_lshlrev_b64 v[20:21], 6, v[0:1]
	global_store_dwordx4 v[28:29], v[22:25], off
	v_mul_f32_e32 v1, v18, v18
	v_fma_f32 v2, v34, v35, -1.0
	v_lshl_add_u64 v[22:23], s[86:87], 0, v[20:21]
	v_lshl_add_u64 v[20:21], s[36:37], 0, v[20:21]
	global_load_dwordx4 v[104:107], v[20:21], off
	global_load_dwordx4 v[108:111], v[20:21], off offset:16
	global_load_dwordx4 v[112:115], v[20:21], off offset:32
	global_load_dwordx4 v[116:119], v[20:21], off offset:48
	global_load_dwordx4 v[120:123], v[22:23], off
	global_load_dwordx4 v[124:127], v[22:23], off offset:16
	global_load_dwordx4 v[128:131], v[22:23], off offset:32
	global_load_dwordx4 v[132:135], v[22:23], off offset:48
	v_readlane_b32 s98, v252, 18
	v_readlane_b32 s99, v252, 19
	v_readlane_b32 s100, v252, 20
	v_readlane_b32 s101, v252, 21
	v_lshlrev_b32_e32 v136, 12, v17
	v_and_b32_e32 v137, 63, v0
	v_lshl_add_u32 v136, v137, 2, v136
	v_mov_b32_e32 v137, 0
	v_lshl_add_u64 v[138:139], s[98:99], 0, v[136:137]
	v_lshl_add_u64 v[140:141], s[100:101], 0, v[136:137]
	global_load_dword v64, v[140:141], off
	global_load_dword v142, v[138:139], off
	global_load_dword v65, v[140:141], off offset:256
	global_load_dword v143, v[138:139], off offset:256
	global_load_dword v66, v[140:141], off offset:512
	global_load_dword v144, v[138:139], off offset:512
	global_load_dword v67, v[140:141], off offset:768
	global_load_dword v145, v[138:139], off offset:768
	global_load_dword v68, v[140:141], off offset:1024
; __device__ __forceinline__ unsigned pk2(float lo, float hi) { return pg8::cvt_pk_bf16(lo, hi); }
; __device__ __forceinline__ void prologue(const Args& a, LAS unsigned char* lds, int tid, int wave, int lane) {
;     ...
;         const float mag = expf(lre * step), ar = mag * cosf(lim * step), ai = mag * sinf(lim * step), den = lre * lre + lim * lim;
;         const float cr = ((ar - 1.f) * lre + ai * lim) / den, ci = (ai * lre - (ar - 1.f) * lim) / den;
;         float pr = ar, pi = ai;
; #pragma unroll
;         for (int k = 0; k < 8; ++k) { const float nr = pr * pr - pi * pi, ni = 2.f * pr * pi; pr = nr; pi = ni; }
;         ((f32x4*)(ws + WS_TA))[i] = (f32x4){ar, ai, pr, pi};
;         bf16_t* tbh = (bf16_t*)(ws + WS_TB) + (size_t)(l * NG + g) * 128 * GC;
;         const float* bre = a.in[I_BRE] + (size_t)i * GC; const float* bim = a.in[I_BIM] + (size_t)i * GC;
; #pragma unroll
;         for (int c = 0; c < GC; c += 2) { const float br0 = bre[c], bi0 = bim[c], br1 = bre[c + 1], bi1 = bim[c + 1];
;             *(unsigned*)(tbh + (2 * p) * GC + c) = pk2(cr * br0 - ci * bi0, cr * br1 - ci * bi1); *(unsigned*)(tbh + (2 * p + 1) * GC + c) = pk2(cr * bi0 + ci * br0, cr * bi1 + ci * br1); }
	global_load_dword v146, v[138:139], off offset:1024
	global_load_dword v69, v[140:141], off offset:1280
	global_load_dword v147, v[138:139], off offset:1280
	global_load_dword v70, v[140:141], off offset:1536
	global_load_dword v148, v[138:139], off offset:1536
	global_load_dword v71, v[140:141], off offset:1792
	global_load_dword v149, v[138:139], off offset:1792
	global_load_dword v72, v[140:141], off offset:2048
	global_load_dword v150, v[138:139], off offset:2048
	global_load_dword v73, v[140:141], off offset:2304
	global_load_dword v151, v[138:139], off offset:2304
	global_load_dword v74, v[140:141], off offset:2560
	global_load_dword v152, v[138:139], off offset:2560
	global_load_dword v75, v[140:141], off offset:2816
	global_load_dword v153, v[138:139], off offset:2816
	global_load_dword v76, v[140:141], off offset:3072
	global_load_dword v154, v[138:139], off offset:3072
	global_load_dword v77, v[140:141], off offset:3328
	global_load_dword v155, v[138:139], off offset:3328
	global_load_dword v78, v[140:141], off offset:3584
	global_load_dword v156, v[138:139], off offset:3584
	global_load_dword v79, v[140:141], off offset:3840
	global_load_dword v157, v[138:139], off offset:3840
	v_mul_f32_e32 v5, v18, v26
	v_fmac_f32_e32 v5, v19, v2
	v_fmac_f32_e32 v1, v19, v19
	v_div_scale_f32 v27, s[0:1], v1, v1, v5
	v_rcp_f32_e32 v30, v27
	v_mul_f32_e32 v2, v18, v2
	v_fma_f32 v2, v19, v26, -v2
	v_readlane_b32 s40, v252, 20
	v_fma_f32 v18, -v27, v30, 1.0
	v_fmac_f32_e32 v30, v18, v30
	v_div_scale_f32 v18, vcc, v5, v1, v5
	v_mul_f32_e32 v19, v18, v30
	v_fma_f32 v26, -v27, v19, v18
	v_fmac_f32_e32 v19, v26, v30
	v_div_scale_f32 v26, s[0:1], v1, v1, v2
	v_fma_f32 v18, -v27, v19, v18
	v_rcp_f32_e32 v27, v26
	v_div_fmas_f32 v18, v18, v30, v19
	v_div_fixup_f32 v5, v18, v1, v5
	v_readlane_b32 s41, v252, 21
	v_fma_f32 v18, -v26, v27, 1.0
	v_fmac_f32_e32 v27, v18, v27
	v_div_scale_f32 v18, vcc, v2, v1, v2
	v_mul_f32_e32 v19, v18, v27
	v_fma_f32 v30, -v26, v19, v18
	v_fmac_f32_e32 v19, v30, v27
	v_fma_f32 v18, -v26, v19, v18
	v_div_fmas_f32 v18, v18, v27, v19
	v_div_fixup_f32 v1, v18, v1, v2
	v_lshlrev_b32_e32 v2, 11, v17
	v_sub_u32_e32 v26, v9, v2
	v_lshl_add_u64 v[18:19], s[12:13], 0, v[6:7]
	v_ashrrev_i32_e32 v27, 31, v26
	v_lshl_add_u64 v[18:19], v[26:27], 1, v[18:19]
	v_add_u32_e32 v9, s22, v9
	v_readlane_b32 s42, v252, 22
	v_readlane_b32 s43, v252, 23
	v_readlane_b32 s44, v252, 24
	v_readlane_b32 s45, v252, 25
	v_readlane_b32 s46, v252, 26
	v_readlane_b32 s47, v252, 27
	v_readlane_b32 s48, v252, 28
	v_readlane_b32 s49, v252, 29
	v_readlane_b32 s50, v252, 30
	v_readlane_b32 s51, v252, 31
	s_waitcnt vmcnt(0)
	v_mov_b64_e32 v[24:25], v[104:105]
	v_mov_b64_e32 v[28:29], v[120:121]
	v_mul_f32_e32 v2, v24, v1
	s_nop 0
	v_fma_f32 v2, v28, v5, -v2
	v_mul_f32_e32 v26, v25, v1
	v_fma_f32 v26, v29, v5, -v26
	v_cvt_pk_bf16_f32 v2, v2, v26
	global_store_dword v[18:19], v2, off
	v_mul_f32_e32 v2, v24, v5
	v_mul_f32_e32 v24, v25, v5
	v_fmac_f32_e32 v2, v28, v1
	v_fmac_f32_e32 v24, v29, v1
	v_cvt_pk_bf16_f32 v2, v2, v24
	v_mov_b64_e32 v[24:25], v[106:107]
	v_mov_b64_e32 v[26:27], v[122:123]
	s_nop 0
	v_mul_f32_e32 v28, v1, v25
	global_store_dword v[18:19], v2, off offset:32
	v_mul_f32_e32 v2, v24, v1
	v_mul_f32_e32 v24, v24, v5
	v_mul_f32_e32 v25, v5, v25
	s_nop 0
	v_fma_f32 v2, v26, v5, -v2
	v_fma_f32 v28, v27, v5, -v28
	v_fmac_f32_e32 v24, v26, v1
	v_fmac_f32_e32 v25, v27, v1
	v_cvt_pk_bf16_f32 v2, v2, v28
	global_store_dword v[18:19], v2, off offset:4
	v_cvt_pk_bf16_f32 v2, v24, v25
	v_mov_b64_e32 v[24:25], v[108:109]
	v_mov_b64_e32 v[26:27], v[124:125]
	s_nop 0
	v_mul_f32_e32 v28, v1, v25
	global_store_dword v[18:19], v2, off offset:36
	v_mul_f32_e32 v2, v1, v24
	v_mul_f32_e32 v24, v5, v24
	v_mul_f32_e32 v25, v5, v25
	s_nop 0
	v_fma_f32 v2, v5, v26, -v2
	v_fma_f32 v28, v5, v27, -v28
	v_fmac_f32_e32 v24, v1, v26
	v_fmac_f32_e32 v25, v1, v27
	v_cvt_pk_bf16_f32 v2, v2, v28
	global_store_dword v[18:19], v2, off offset:8
	v_cvt_pk_bf16_f32 v2, v24, v25
	v_mov_b64_e32 v[24:25], v[110:111]
	v_mov_b64_e32 v[26:27], v[126:127]
	s_nop 0
	v_mul_f32_e32 v28, v1, v25
	global_store_dword v[18:19], v2, off offset:40
	v_mul_f32_e32 v2, v1, v24
	v_mul_f32_e32 v24, v5, v24
	v_mul_f32_e32 v25, v5, v25
	s_nop 0
	v_fma_f32 v2, v5, v26, -v2
	v_fma_f32 v28, v5, v27, -v28
	v_fmac_f32_e32 v24, v1, v26
	v_fmac_f32_e32 v25, v1, v27
	v_cvt_pk_bf16_f32 v2, v2, v28
	global_store_dword v[18:19], v2, off offset:12
	v_cvt_pk_bf16_f32 v2, v24, v25
	v_mov_b64_e32 v[24:25], v[112:113]
	v_mov_b64_e32 v[26:27], v[128:129]
	s_nop 0
	v_mul_f32_e32 v28, v1, v25
	global_store_dword v[18:19], v2, off offset:44
	v_mul_f32_e32 v2, v1, v24
	v_mul_f32_e32 v24, v5, v24
	v_mul_f32_e32 v25, v5, v25
	s_nop 0
	v_fma_f32 v2, v5, v26, -v2
	v_fma_f32 v28, v5, v27, -v28
	v_fmac_f32_e32 v24, v1, v26
	v_fmac_f32_e32 v25, v1, v27
	v_cvt_pk_bf16_f32 v2, v2, v28
	global_store_dword v[18:19], v2, off offset:16
	v_cvt_pk_bf16_f32 v2, v24, v25
	v_mov_b64_e32 v[24:25], v[114:115]
	v_mov_b64_e32 v[26:27], v[130:131]
	s_nop 0
	v_mul_f32_e32 v28, v1, v25
	global_store_dword v[18:19], v2, off offset:48
	v_mul_f32_e32 v2, v1, v24
	v_mul_f32_e32 v24, v5, v24
	v_mul_f32_e32 v25, v5, v25
	s_nop 0
	v_fma_f32 v2, v5, v26, -v2
	v_fma_f32 v28, v5, v27, -v28
	v_fmac_f32_e32 v24, v1, v26
	v_fmac_f32_e32 v25, v1, v27
	v_cvt_pk_bf16_f32 v2, v2, v28
	global_store_dword v[18:19], v2, off offset:20
	v_cvt_pk_bf16_f32 v2, v24, v25
	v_mov_b64_e32 v[24:25], v[116:117]
	v_mov_b64_e32 v[26:27], v[132:133]
	s_nop 0
	v_mul_f32_e32 v28, v1, v25
	global_store_dword v[18:19], v2, off offset:52
	v_mul_f32_e32 v2, v1, v24
	s_nop 0
	v_fma_f32 v2, v5, v26, -v2
; __device__ __forceinline__ unsigned pk2(float lo, float hi) { return pg8::cvt_pk_bf16(lo, hi); }
; __device__ __forceinline__ void prologue(const Args& a, LAS unsigned char* lds, int tid, int wave, int lane) {
;     ...
;         for (int c = 0; c < GC; c += 2) { const float br0 = bre[c], bi0 = bim[c], br1 = bre[c + 1], bi1 = bim[c + 1];
;             *(unsigned*)(tbh + (2 * p) * GC + c) = pk2(cr * br0 - ci * bi0, cr * br1 - ci * bi1); *(unsigned*)(tbh + (2 * p + 1) * GC + c) = pk2(cr * bi0 + ci * br0, cr * bi1 + ci * br1); }
;         bf16_t* tc = (bf16_t*)(ws + WS_TC) + (size_t)(l * NG + g) * GC * 128;
;         const float* cre = a.in[I_CRE] + (size_t)(l * NG + g) * GC * NP; const float* cim = a.in[I_CIM] + (size_t)(l * NG + g) * GC * NP;
; #pragma unroll
;         for (int c = 0; c < GC; ++c) *(unsigned*)(tc + c * 128 + 2 * p) = pk2(cre[c * NP + p], -cim[c * NP + p]);
	v_mul_f32_e32 v24, v5, v24
	v_mul_f32_e32 v25, v5, v25
	v_fma_f32 v28, v5, v27, -v28
	v_cvt_pk_bf16_f32 v2, v2, v28
	v_fmac_f32_e32 v24, v1, v26
	v_fmac_f32_e32 v25, v1, v27
	global_store_dword v[18:19], v2, off offset:24
	v_cvt_pk_bf16_f32 v2, v24, v25
	v_mov_b64_e32 v[20:21], v[118:119]
	s_nop 0
	v_mov_b64_e32 v[22:23], v[134:135]
	v_lshlrev_b32_e32 v24, 6, v17
	v_sub_u32_e32 v24, v0, v24
	v_ashrrev_i32_e32 v25, 31, v24
	v_lshl_add_u64 v[26:27], s[38:39], 0, v[6:7]
	v_lshl_add_u64 v[28:29], s[40:41], 0, v[6:7]
	v_lshlrev_b64 v[30:31], 2, v[24:25]
	global_store_dword v[18:19], v2, off offset:56
	v_lshl_add_u64 v[32:33], v[26:27], 0, v[30:31]
	v_lshl_add_u64 v[30:31], v[28:29], 0, v[30:31]
	v_lshl_add_u64 v[6:7], s[14:15], 0, v[6:7]
	v_add_u32_e32 v0, s3, v0
	v_cmp_lt_i32_e32 vcc, s53, v0
	s_or_b64 s[16:17], vcc, s[16:17]
	s_nop 0
	v_mul_f32_e32 v2, v1, v20
	v_mul_f32_e32 v25, v1, v21
	v_mul_f32_e32 v20, v5, v20
	v_mul_f32_e32 v21, v5, v21
	s_nop 0
	v_fma_f32 v2, v5, v22, -v2
	v_fma_f32 v5, v5, v23, -v25
	v_fmac_f32_e32 v20, v1, v22
	v_fmac_f32_e32 v21, v1, v23
	v_cvt_pk_bf16_f32 v1, v2, v5
	global_store_dword v[18:19], v1, off offset:28
	v_cvt_pk_bf16_f32 v1, v20, v21
	v_mov_b32_e32 v5, v64
	v_mov_b32_e32 v25, v142
	v_add_u32_e32 v2, 64, v24
	v_lshlrev_b64 v[20:21], 2, v[2:3]
	v_lshl_add_u64 v[22:23], v[26:27], 0, v[20:21]
	v_lshl_add_u64 v[20:21], v[28:29], 0, v[20:21]
	global_store_dword v[18:19], v1, off offset:60
	v_lshlrev_b32_e32 v2, 7, v17
	v_sub_u32_e32 v18, v10, v2
	v_ashrrev_i32_e32 v19, 31, v18
	v_add_u32_e32 v2, 0x80, v24
	v_lshl_add_u64 v[6:7], v[18:19], 1, v[6:7]
	v_lshlrev_b64 v[18:19], 2, v[2:3]
	v_add_u32_e32 v2, 0xc0, v24
	v_add_u32_e32 v10, s23, v10
	s_nop 0
	v_xor_b32_e32 v1, 0x80000000, v5
	s_nop 0
	v_cvt_pk_bf16_f32 v1, v25, v1
	v_mov_b32_e32 v5, v65
	s_nop 0
	v_mov_b32_e32 v22, v143
	v_lshl_add_u64 v[20:21], v[26:27], 0, v[18:19]
	v_lshl_add_u64 v[18:19], v[28:29], 0, v[18:19]
	global_store_dword v[6:7], v1, off
	s_nop 0
	v_xor_b32_e32 v1, 0x80000000, v5
	s_nop 0
	v_cvt_pk_bf16_f32 v1, v22, v1
	v_mov_b32_e32 v5, v66
	v_mov_b32_e32 v17, v144
	v_lshlrev_b64 v[18:19], 2, v[2:3]
	v_lshl_add_u64 v[20:21], v[26:27], 0, v[18:19]
	v_lshl_add_u64 v[18:19], v[28:29], 0, v[18:19]
	global_store_dword v[6:7], v1, off offset:256
	v_add_u32_e32 v2, 0x100, v24
	s_nop 0
	v_xor_b32_e32 v1, 0x80000000, v5
	s_nop 0
	v_cvt_pk_bf16_f32 v1, v17, v1
	v_mov_b32_e32 v5, v67
	v_mov_b32_e32 v17, v145
	v_lshlrev_b64 v[18:19], 2, v[2:3]
	v_lshl_add_u64 v[20:21], v[26:27], 0, v[18:19]
	v_lshl_add_u64 v[18:19], v[28:29], 0, v[18:19]
	global_store_dword v[6:7], v1, off offset:512
	v_add_u32_e32 v2, 0x140, v24
	s_nop 0
	v_xor_b32_e32 v1, 0x80000000, v5
	s_nop 0
	v_cvt_pk_bf16_f32 v1, v17, v1
	v_mov_b32_e32 v5, v68
	v_mov_b32_e32 v17, v146
	v_lshlrev_b64 v[18:19], 2, v[2:3]
	v_lshl_add_u64 v[20:21], v[26:27], 0, v[18:19]
	v_lshl_add_u64 v[18:19], v[28:29], 0, v[18:19]
	global_store_dword v[6:7], v1, off offset:768
	v_add_u32_e32 v2, 0x180, v24
	s_nop 0
	v_xor_b32_e32 v1, 0x80000000, v5
	s_nop 0
	v_cvt_pk_bf16_f32 v1, v17, v1
	v_mov_b32_e32 v5, v69
	v_mov_b32_e32 v17, v147
	v_lshlrev_b64 v[18:19], 2, v[2:3]
	v_lshl_add_u64 v[20:21], v[26:27], 0, v[18:19]
	v_lshl_add_u64 v[18:19], v[28:29], 0, v[18:19]
	global_store_dword v[6:7], v1, off offset:1024
	v_add_u32_e32 v2, 0x1c0, v24
	s_nop 0
	v_xor_b32_e32 v1, 0x80000000, v5
	s_nop 0
	v_cvt_pk_bf16_f32 v1, v17, v1
	v_mov_b32_e32 v5, v70
	v_mov_b32_e32 v17, v148
	v_lshlrev_b64 v[18:19], 2, v[2:3]
	v_lshl_add_u64 v[20:21], v[26:27], 0, v[18:19]
	v_lshl_add_u64 v[18:19], v[28:29], 0, v[18:19]
	global_store_dword v[6:7], v1, off offset:1280
	v_add_u32_e32 v2, 0x200, v24
	s_nop 0
	v_xor_b32_e32 v1, 0x80000000, v5
	s_nop 0
	v_cvt_pk_bf16_f32 v1, v17, v1
	v_mov_b32_e32 v5, v71
	v_mov_b32_e32 v17, v149
	v_lshlrev_b64 v[18:19], 2, v[2:3]
	v_lshl_add_u64 v[20:21], v[26:27], 0, v[18:19]
	v_lshl_add_u64 v[18:19], v[28:29], 0, v[18:19]
	global_store_dword v[6:7], v1, off offset:1536
	v_add_u32_e32 v2, 0x240, v24
	s_nop 0
	v_xor_b32_e32 v1, 0x80000000, v5
	s_nop 0
	v_cvt_pk_bf16_f32 v1, v17, v1
	v_mov_b32_e32 v5, v72
	v_mov_b32_e32 v17, v150
	v_lshlrev_b64 v[18:19], 2, v[2:3]
	v_lshl_add_u64 v[20:21], v[26:27], 0, v[18:19]
	v_lshl_add_u64 v[18:19], v[28:29], 0, v[18:19]
	global_store_dword v[6:7], v1, off offset:1792
	v_add_u32_e32 v2, 0x280, v24
	s_nop 0
	v_xor_b32_e32 v1, 0x80000000, v5
	s_nop 0
	v_cvt_pk_bf16_f32 v1, v17, v1
	v_mov_b32_e32 v5, v73
	v_mov_b32_e32 v17, v151
	v_lshlrev_b64 v[18:19], 2, v[2:3]
	v_lshl_add_u64 v[20:21], v[26:27], 0, v[18:19]
	v_lshl_add_u64 v[18:19], v[28:29], 0, v[18:19]
	global_store_dword v[6:7], v1, off offset:2048
	v_add_u32_e32 v2, 0x2c0, v24
	s_nop 0
	v_xor_b32_e32 v1, 0x80000000, v5
	s_nop 0
	v_cvt_pk_bf16_f32 v1, v17, v1
	v_mov_b32_e32 v5, v74
	v_mov_b32_e32 v17, v152
	v_lshlrev_b64 v[18:19], 2, v[2:3]
	v_lshl_add_u64 v[20:21], v[26:27], 0, v[18:19]
	v_lshl_add_u64 v[18:19], v[28:29], 0, v[18:19]
	global_store_dword v[6:7], v1, off offset:2304
	v_add_u32_e32 v2, 0x300, v24
	s_nop 0
	v_xor_b32_e32 v1, 0x80000000, v5
	s_nop 0
	v_cvt_pk_bf16_f32 v1, v17, v1
	v_mov_b32_e32 v5, v75
	v_mov_b32_e32 v17, v153
	v_lshlrev_b64 v[18:19], 2, v[2:3]
	v_lshl_add_u64 v[20:21], v[26:27], 0, v[18:19]
	v_lshl_add_u64 v[18:19], v[28:29], 0, v[18:19]
	global_store_dword v[6:7], v1, off offset:2560
	v_add_u32_e32 v2, 0x340, v24
	s_nop 0
	v_xor_b32_e32 v1, 0x80000000, v5
	s_nop 0
	v_cvt_pk_bf16_f32 v1, v17, v1
	v_mov_b32_e32 v5, v76
	v_mov_b32_e32 v17, v154
	v_lshlrev_b64 v[18:19], 2, v[2:3]
	v_lshl_add_u64 v[20:21], v[26:27], 0, v[18:19]
	v_lshl_add_u64 v[18:19], v[28:29], 0, v[18:19]
	global_store_dword v[6:7], v1, off offset:2816
	v_add_u32_e32 v2, 0x380, v24
	s_nop 0
	v_xor_b32_e32 v1, 0x80000000, v5
	s_nop 0
	v_cvt_pk_bf16_f32 v1, v17, v1
	v_mov_b32_e32 v5, v77
	v_mov_b32_e32 v17, v155
	v_lshlrev_b64 v[18:19], 2, v[2:3]
	v_lshl_add_u64 v[20:21], v[26:27], 0, v[18:19]
	v_lshl_add_u64 v[18:19], v[28:29], 0, v[18:19]
	global_store_dword v[6:7], v1, off offset:3072
	v_add_u32_e32 v2, 0x3c0, v24
	s_nop 0
	v_xor_b32_e32 v1, 0x80000000, v5
	s_nop 0
	v_cvt_pk_bf16_f32 v1, v17, v1
	v_mov_b32_e32 v5, v78
	v_mov_b32_e32 v17, v156
	v_lshlrev_b64 v[18:19], 2, v[2:3]
	v_lshl_add_u64 v[20:21], v[26:27], 0, v[18:19]
	v_lshl_add_u64 v[18:19], v[28:29], 0, v[18:19]
	global_store_dword v[6:7], v1, off offset:3328
	s_nop 0
	v_xor_b32_e32 v1, 0x80000000, v5
	s_nop 0
	v_cvt_pk_bf16_f32 v1, v17, v1
	v_mov_b32_e32 v2, v79
	v_mov_b32_e32 v5, v157
	s_nop 0
	global_store_dword v[6:7], v1, off offset:3584
	s_nop 0
	v_xor_b32_e32 v1, 0x80000000, v2
	s_nop 0
	v_cvt_pk_bf16_f32 v1, v5, v1
	global_store_dword v[6:7], v1, off offset:3840
	s_andn2_b64 exec, exec, s[16:17]
	s_cbranch_execz .LBB0_150

; __device__ __forceinline__ int opq(int v) { asm volatile("" : "+v"(v)); return v; }
; __global__ void __launch_bounds__(512, 2) mk_fwd(Args a) {
;     ...
;         {   SsmTab T; ssm_tables<true>(a, l, bx & 3, wave, T); u32x4 pre[2];
;             for (int u = bx; u < NBATCH * NSEG * 4; u += G) { const int gq = u & 3, seg = (u >> 2) % NSEG, b = (u >> 2) / NSEG;
;                 const size_t r0 = (size_t)b * SEQ + (size_t)seg * (SEGB * SBLK); const int lane = opq(threadIdx.x) & 63, g = gq * 8 + wave;
;                 ssm_stage_load(a, r0, SBLK, gq, pre);
;                 float hr = 0.f, hi = 0.f;
;                 {
;                     float2 e[NSEG - 1];
; #pragma unroll
;                     for (int i = 0; i < NSEG - 1; ++i) e[i] = (i < seg) ? *(const float2*)(Ebuf + ((((size_t)b * NSEG + i) * NG + g) * NP + lane) * 2) : make_float2(0.f, 0.f);
; #pragma unroll
;                     for (int i = 0; i < NSEG - 1; ++i) if (i < seg) { const float nr = T.ta[2] * hr - T.ta[3] * hi + e[i].x, ni = T.ta[2] * hi + T.ta[3] * hr + e[i].y; hr = nr; hi = ni; } }
; #pragma unroll 1
;                 for (int blk = 0; blk < SEGB; ++blk) { u32x4 cur[2] = {pre[0], pre[1]};
;                     if (blk + 1 < SEGB) ssm_stage_load(a, r0 + (blk + 1) * SBLK, SBLK, gq, pre);
;                     ssm_unit<true>(a, lds, T, cur, l, r0 + blk * SBLK, SBLK, gq, hr, hi, wave); }
;                 if (seg == NSEG - 1) { const size_t so = ((size_t)l * NBATCH + b) * NG * NP + g * NP + lane; a.out[O_HRP + so] = hr; a.out[O_HIP + so] = hi; } }
;             for (int v = bx; v < DEC_B * 4; v += G) { const int gq = v & 3, b = v >> 2; const int lane = opq(threadIdx.x) & 63, g = gq * 8 + wave;
;                 const size_t so = ((size_t)l * DEC_B + b) * NG * NP + g * NP + lane;
;                 ssm_stage_load(a, (size_t)NTOK_P + b * DEC_T, DEC_T, gq, pre);
;                 float hr = a.in[I_SR][so], hi = a.in[I_SI][so];
;                 ssm_unit<true>(a, lds, T, pre, l, (size_t)NTOK_P + b * DEC_T, DEC_T, gq, hr, hi, wave);
;                 a.out[O_HRS + so] = hr; a.out[O_HIS + so] = hi; } }
.LBB0_472:
	s_add_u32 s6, s6, 0x10000
	s_addc_u32 s7, s7, 0
	s_cmp_eq_u32 s12, 3
	s_cbranch_scc0 .Lssp_skip
	v_readlane_b32 s98, v255, 41
	s_and_b32 s99, s2, 0xff
	s_lshl_b32 s98, s98, 18
	s_lshr_b32 s100, s99, 2
	s_and_b32 s99, s99, 3
	s_lshl_b32 s100, s100, 11
	s_lshl_b32 s99, s99, 9
	s_add_i32 s98, s98, s100
	s_add_i32 s98, s98, s99
	v_add_u32_e32 v236, s98, v184
	v_lshlrev_b32_e32 v236, 2, v236
	v_mov_b32_e32 v237, 0
	v_readlane_b32 s98, v252, 8
	v_readlane_b32 s99, v252, 9
	v_readlane_b32 s100, v252, 10
	v_readlane_b32 s101, v252, 11
	s_nop 1
	v_lshl_add_u64 v[238:239], s[98:99], 0, v[236:237]
	v_lshl_add_u64 v[240:241], s[100:101], 0, v[236:237]
	global_load_dword v242, v[238:239], off
	global_load_dword v243, v[240:241], off
	v_add_u32_e32 v236, 0x80000, v236
	v_lshl_add_u64 v[238:239], s[98:99], 0, v[236:237]
	v_lshl_add_u64 v[240:241], s[100:101], 0, v[236:237]
	global_load_dword v244, v[238:239], off
	global_load_dword v245, v[240:241], off
